# EpiF32 GEMM loop: merge phases 3+4 and 7+8 (12 barriers/iter), rest as v19
# speedup vs baseline: 1.0358x; 1.0032x over previous
; #define PG8_STAGE(bufoff, gbase, voff) do { _Pragma("unroll") for (int _i = 0; _i < 2; ++_i) \
;         __builtin_amdgcn_global_load_lds((const unsigned*)((const char*)(gbase) + (voff)[_i]), (LAS unsigned*)(lds + (bufoff) + ldsw + _i * 8192), 16, 0, 0); } while (0)
; #define PG8_LDA(dst, b, h) do { _Pragma("unroll") for (int m = 0; m < 4; ++m) _Pragma("unroll") for (int k = 0; k < 2; ++k) dst[m][k] = *(const LAS bf16x8*)(lds + PG8_SA(b, h) + aoff + m * 2048 + k * 1024); } while (0)
; #define PG8_LDB(dst, b, h) do { _Pragma("unroll") for (int n = 0; n < 2; ++n) _Pragma("unroll") for (int k = 0; k < 2; ++k) dst[n][k] = *(const LAS bf16x8*)(lds + PG8_SB(b, h) + boff + n * 2048 + k * 1024); } while (0)
; #define PG8_MMA(ai, bj, At, Bt) do { __builtin_amdgcn_s_setprio(1); _Pragma("unroll") for (int m = 0; m < 4; ++m) _Pragma("unroll") for (int n = 0; n < 2; ++n) _Pragma("unroll") for (int k = 0; k < 2; ++k) \
;         acc[ai][bj][m][n] = __builtin_amdgcn_mfma_f32_16x16x32_bf16(Bt[n][k], At[m][k], acc[ai][bj][m][n], 0, 0, 0); __builtin_amdgcn_s_setprio(0); } while (0)
; #define PG8_WAIT_V(n) asm volatile("s_waitcnt vmcnt(" #n ")" ::: "memory")
; template <class Epi>
; __device__ __forceinline__ void gemm_phase(LAS unsigned char* lds, const Gemm g, const Sched& S, const Epi& E) {
;     ...
;         for (int t = 0; t < nt; t += 2) {
;             const bool last = (t == nt - 2);
;             const char* a1 = cA + (size_t)(t + 1) * kstep;
;             const char* a2 = last ? nA : cA + (size_t)(t + 2) * kstep; const char* b2 = last ? nB : cB + (size_t)(t + 2) * kstep;
;             const char* a3 = a2 + kstep; const char* b3 = b2 + kstep;
;             PG8_LDB(B0, 0, 0); PG8_SCHED; PG8_LDA(At, 0, 0); PG8_STAGE(PG8_SA(1, 1), a1 + hstepA, voffA);
;             PG8_WAIT_L(8); PG8_BAR; PG8_WAIT_L(0); PG8_MMA(0, 0, At, B0); PG8_BAR; PG8_SCHED;
;             PG8_LDB(B1, 0, 1); PG8_STAGE(PG8_SB(0, 0), b2, voffB);
;             PG8_BAR; PG8_WAIT_L(0); PG8_MMA(0, 1, At, B1); PG8_BAR;
;             PG8_LDA(At, 0, 1); PG8_STAGE(PG8_SA(0, 0), a2, voffA);
;             PG8_BAR; PG8_WAIT_L(0); PG8_MMA(1, 0, At, B0); PG8_BAR; PG8_SCHED;
;             PG8_STAGE(PG8_SB(0, 1), b2 + hstepB, voffB);
;             PG8_WAIT_V(6); PG8_BAR; PG8_MMA(1, 1, At, B1); PG8_BAR;
;             PG8_LDB(B0, 1, 0); PG8_SCHED; PG8_LDA(At, 1, 0); PG8_STAGE(PG8_SA(0, 1), a2 + hstepA, voffA);
.Lresync_y_719:
.LBB0_719:
	s_add_i32 s14, s4, 2
	s_add_u32 s15, s0, 0x80
	s_addc_u32 s5, s1, 0
	s_add_i32 s8, 0, 0x10000
	v_add_u32_e32 v118, s8, v217
	ds_read_b128 v[106:109], v118
	ds_read_b128 v[110:113], v118 offset:1024
	ds_read_b128 v[114:117], v118 offset:2048
	ds_read_b128 v[118:121], v118 offset:3072
	s_cmp_eq_u32 s48, s4
	s_cselect_b32 s4, s59, s15
	s_cselect_b32 s5, s57, s5
	s_cselect_b32 s95, vcc_lo, s35
	s_cselect_b32 s94, vcc_hi, s34
	v_lshl_add_u64 v[154:155], s[0:1], 0, v[202:203]
	s_add_i32 m0, s52, 0xc000
	ds_read_b128 v[122:125], v235
	ds_read_b128 v[126:129], v235 offset:1024
	ds_read_b128 v[130:133], v235 offset:2048
	ds_read_b128 v[134:137], v235 offset:3072
	ds_read_b128 v[138:141], v235 offset:4096
	ds_read_b128 v[142:145], v235 offset:5120
	ds_read_b128 v[146:149], v235 offset:6144
	ds_read_b128 v[150:153], v235 offset:7168
	global_load_lds_dwordx4 v[154:155], off
	v_lshl_add_u64 v[154:155], s[0:1], 0, v[204:205]
	s_add_i32 m0, s52, 0xe000
	s_nop 0
	global_load_lds_dwordx4 v[154:155], off
	s_waitcnt lgkmcnt(8)
	s_waitcnt lgkmcnt(0)
	v_mfma_f32_16x16x32_bf16 v[162:165], v[114:117], v[130:133], v[162:165]
	v_mfma_f32_16x16x32_bf16 v[94:97], v[106:109], v[138:141], v[94:97]
	v_mfma_f32_16x16x32_bf16 v[90:93], v[114:117], v[138:141], v[90:93]
	v_mfma_f32_16x16x32_bf16 v[78:81], v[106:109], v[146:149], v[78:81]
	s_barrier
	s_waitcnt lgkmcnt(0)
	s_setprio 1
	s_waitcnt lgkmcnt(0)
	v_mfma_f32_16x16x32_bf16 v[74:77], v[114:117], v[146:149], v[74:77]
	v_mfma_f32_16x16x32_bf16 v[154:157], v[106:109], v[122:125], v[190:193]
	v_mfma_f32_16x16x32_bf16 v[158:161], v[114:117], v[122:125], v[186:189]
	v_mfma_f32_16x16x32_bf16 v[166:169], v[106:109], v[130:133], v[174:177]
	v_mfma_f32_16x16x32_bf16 v[162:165], v[118:121], v[134:137], v[162:165]
	v_mfma_f32_16x16x32_bf16 v[94:97], v[110:113], v[142:145], v[94:97]
	v_mfma_f32_16x16x32_bf16 v[90:93], v[118:121], v[142:145], v[90:93]
	v_mfma_f32_16x16x32_bf16 v[78:81], v[110:113], v[150:153], v[78:81]
	v_mfma_f32_16x16x32_bf16 v[74:77], v[118:121], v[150:153], v[74:77]
	v_mfma_f32_16x16x32_bf16 v[154:157], v[110:113], v[126:129], v[154:157]
	v_mfma_f32_16x16x32_bf16 v[158:161], v[118:121], v[126:129], v[158:161]
	v_mfma_f32_16x16x32_bf16 v[166:169], v[110:113], v[134:137], v[166:169]
	s_setprio 0
	s_barrier
	s_add_i32 s9, 0, 0x14000
	s_add_i32 s8, s8, s43
	v_add_u32_e32 v190, s9, v217
	v_lshl_add_u64 v[210:211], s[94:95], 0, v[0:1]
	s_mov_b32 m0, s8
	ds_read_b128 v[170:173], v190
	ds_read_b128 v[174:177], v190 offset:1024
	ds_read_b128 v[186:189], v190 offset:2048
	ds_read_b128 v[190:193], v190 offset:3072
	global_load_lds_dwordx4 v[210:211], off
	v_lshl_add_u64 v[212:213], s[94:95], 0, v[200:201]
	s_add_i32 m0, s8, 0x2000
	s_nop 0
	global_load_lds_dwordx4 v[212:213], off
	s_waitcnt lgkmcnt(0)
	v_mfma_f32_16x16x32_bf16 v[182:185], v[170:173], v[122:125], v[182:185]
	v_mfma_f32_16x16x32_bf16 v[102:105], v[170:173], v[130:133], v[102:105]
	v_mfma_f32_16x16x32_bf16 v[98:101], v[186:189], v[130:133], v[98:101]
	v_mfma_f32_16x16x32_bf16 v[86:89], v[170:173], v[138:141], v[86:89]
	s_barrier
	s_waitcnt lgkmcnt(0)
	s_setprio 1
	s_waitcnt lgkmcnt(0)
	v_mfma_f32_16x16x32_bf16 v[82:85], v[186:189], v[138:141], v[82:85]
	v_mfma_f32_16x16x32_bf16 v[70:73], v[170:173], v[146:149], v[70:73]
	v_mfma_f32_16x16x32_bf16 v[66:69], v[186:189], v[146:149], v[66:69]
	v_mfma_f32_16x16x32_bf16 v[182:185], v[174:177], v[126:129], v[182:185]
	v_mfma_f32_16x16x32_bf16 v[122:125], v[186:189], v[122:125], v[178:181]
	v_mfma_f32_16x16x32_bf16 v[102:105], v[174:177], v[134:137], v[102:105]
	v_mfma_f32_16x16x32_bf16 v[98:101], v[190:193], v[134:137], v[98:101]
	v_mfma_f32_16x16x32_bf16 v[86:89], v[174:177], v[142:145], v[86:89]
	v_mfma_f32_16x16x32_bf16 v[82:85], v[190:193], v[142:145], v[82:85]
	v_mfma_f32_16x16x32_bf16 v[70:73], v[174:177], v[150:153], v[70:73]
	v_mfma_f32_16x16x32_bf16 v[66:69], v[190:193], v[150:153], v[66:69]
	v_mfma_f32_16x16x32_bf16 v[122:125], v[190:193], v[126:129], v[122:125]
	s_setprio 0
	s_mov_b32 m0, s52
	v_lshl_add_u64 v[214:215], s[4:5], 0, v[196:197]
	s_barrier
	ds_read_b128 v[126:129], v235 offset:16384
	ds_read_b128 v[130:133], v235 offset:17408
	ds_read_b128 v[134:137], v235 offset:18432
	ds_read_b128 v[138:141], v235 offset:19456
	ds_read_b128 v[142:145], v235 offset:20480
	ds_read_b128 v[146:149], v235 offset:21504
	ds_read_b128 v[150:153], v235 offset:22528
	ds_read_b128 v[178:181], v235 offset:23552
	global_load_lds_dwordx4 v[214:215], off
	v_lshl_add_u64 v[222:223], s[4:5], 0, v[198:199]
	s_mov_b32 m0, s53
	s_nop 0
	global_load_lds_dwordx4 v[222:223], off
	s_add_u32 s94, s94, s76
	s_addc_u32 s95, s95, s77
	s_add_i32 s8, s9, s43
	v_lshl_add_u64 v[224:225], s[94:95], 0, v[0:1]
	s_mov_b32 m0, s8
	v_lshl_add_u64 v[226:227], s[94:95], 0, v[200:201]
	global_load_lds_dwordx4 v[224:225], off
	s_add_i32 m0, s8, 0x2000
	s_nop 0
	global_load_lds_dwordx4 v[226:227], off
	s_waitcnt vmcnt(6)
	s_waitcnt lgkmcnt(0)
	v_mfma_f32_16x16x32_bf16 v[62:65], v[106:109], v[126:129], v[62:65]
	v_mfma_f32_16x16x32_bf16 v[58:61], v[114:117], v[126:129], v[58:61]
	v_mfma_f32_16x16x32_bf16 v[46:49], v[106:109], v[134:137], v[46:49]
	v_mfma_f32_16x16x32_bf16 v[42:45], v[114:117], v[134:137], v[42:45]
	s_barrier
; #define PG8_STAGE(bufoff, gbase, voff) do { _Pragma("unroll") for (int _i = 0; _i < 2; ++_i) \
;         __builtin_amdgcn_global_load_lds((const unsigned*)((const char*)(gbase) + (voff)[_i]), (LAS unsigned*)(lds + (bufoff) + ldsw + _i * 8192), 16, 0, 0); } while (0)
; #define PG8_LDA(dst, b, h) do { _Pragma("unroll") for (int m = 0; m < 4; ++m) _Pragma("unroll") for (int k = 0; k < 2; ++k) dst[m][k] = *(const LAS bf16x8*)(lds + PG8_SA(b, h) + aoff + m * 2048 + k * 1024); } while (0)
; #define PG8_LDB(dst, b, h) do { _Pragma("unroll") for (int n = 0; n < 2; ++n) _Pragma("unroll") for (int k = 0; k < 2; ++k) dst[n][k] = *(const LAS bf16x8*)(lds + PG8_SB(b, h) + boff + n * 2048 + k * 1024); } while (0)
; #define PG8_MMA(ai, bj, At, Bt) do { __builtin_amdgcn_s_setprio(1); _Pragma("unroll") for (int m = 0; m < 4; ++m) _Pragma("unroll") for (int n = 0; n < 2; ++n) _Pragma("unroll") for (int k = 0; k < 2; ++k) \
;         acc[ai][bj][m][n] = __builtin_amdgcn_mfma_f32_16x16x32_bf16(Bt[n][k], At[m][k], acc[ai][bj][m][n], 0, 0, 0); __builtin_amdgcn_s_setprio(0); } while (0)
; #define PG8_WAIT_V(n) asm volatile("s_waitcnt vmcnt(" #n ")" ::: "memory")
; #define PG8_WAIT_L(n) asm volatile("s_waitcnt lgkmcnt(" #n ")" ::: "memory")
; #define PG8_BAR __builtin_amdgcn_s_barrier()
; #define PG8_SCHED __builtin_amdgcn_sched_barrier(0)
; template <class Epi>
; __device__ __forceinline__ void gemm_phase(LAS unsigned char* lds, const Gemm g, const Sched& S, const Epi& E) {
;     ...
;             PG8_LDA(At, 0, 1); PG8_STAGE(PG8_SA(0, 0), a2, voffA);
;             PG8_BAR; PG8_WAIT_L(0); PG8_MMA(1, 0, At, B0); PG8_BAR; PG8_SCHED;
;             PG8_STAGE(PG8_SB(0, 1), b2 + hstepB, voffB);
;             PG8_WAIT_V(6); PG8_BAR; PG8_MMA(1, 1, At, B1); PG8_BAR;
;             PG8_LDB(B0, 1, 0); PG8_SCHED; PG8_LDA(At, 1, 0); PG8_STAGE(PG8_SA(0, 1), a2 + hstepA, voffA);
;             PG8_WAIT_L(8); PG8_BAR; PG8_WAIT_L(0); PG8_MMA(0, 0, At, B0); PG8_BAR; PG8_SCHED;
;             PG8_LDB(B1, 1, 1); PG8_STAGE(PG8_SB(1, 0), b3, voffB);
;             PG8_BAR; PG8_WAIT_L(0); PG8_MMA(0, 1, At, B1); PG8_BAR;
;             PG8_LDA(At, 1, 1); PG8_STAGE(PG8_SA(1, 0), a3, voffA);
	s_setprio 1
	v_mfma_f32_16x16x32_bf16 v[30:33], v[106:109], v[142:145], v[30:33]
	v_mfma_f32_16x16x32_bf16 v[26:29], v[114:117], v[142:145], v[26:29]
	v_mfma_f32_16x16x32_bf16 v[14:17], v[106:109], v[150:153], v[14:17]
	v_mfma_f32_16x16x32_bf16 v[10:13], v[114:117], v[150:153], v[10:13]
	v_mfma_f32_16x16x32_bf16 v[62:65], v[110:113], v[130:133], v[62:65]
	v_mfma_f32_16x16x32_bf16 v[58:61], v[118:121], v[130:133], v[58:61]
	v_mfma_f32_16x16x32_bf16 v[46:49], v[110:113], v[138:141], v[46:49]
	v_mfma_f32_16x16x32_bf16 v[42:45], v[118:121], v[138:141], v[42:45]
	v_mfma_f32_16x16x32_bf16 v[30:33], v[110:113], v[146:149], v[30:33]
	v_mfma_f32_16x16x32_bf16 v[26:29], v[118:121], v[146:149], v[26:29]
	v_mfma_f32_16x16x32_bf16 v[14:17], v[110:113], v[178:181], v[14:17]
	v_mfma_f32_16x16x32_bf16 v[10:13], v[118:121], v[178:181], v[10:13]
	v_mfma_f32_16x16x32_bf16 v[54:57], v[170:173], v[126:129], v[54:57]
	v_mfma_f32_16x16x32_bf16 v[50:53], v[186:189], v[126:129], v[50:53]
	v_mfma_f32_16x16x32_bf16 v[38:41], v[170:173], v[134:137], v[38:41]
	v_mfma_f32_16x16x32_bf16 v[34:37], v[186:189], v[134:137], v[34:37]
	v_mfma_f32_16x16x32_bf16 v[22:25], v[170:173], v[142:145], v[22:25]
	v_mfma_f32_16x16x32_bf16 v[18:21], v[186:189], v[142:145], v[18:21]
	v_mfma_f32_16x16x32_bf16 v[6:9], v[170:173], v[150:153], v[6:9]
	v_mfma_f32_16x16x32_bf16 v[2:5], v[186:189], v[150:153], v[2:5]
	v_mfma_f32_16x16x32_bf16 v[54:57], v[174:177], v[130:133], v[54:57]
	v_mfma_f32_16x16x32_bf16 v[50:53], v[190:193], v[130:133], v[50:53]
	v_mfma_f32_16x16x32_bf16 v[38:41], v[174:177], v[138:141], v[38:41]
	v_mfma_f32_16x16x32_bf16 v[34:37], v[190:193], v[138:141], v[34:37]
	v_mfma_f32_16x16x32_bf16 v[22:25], v[174:177], v[146:149], v[22:25]
	v_mfma_f32_16x16x32_bf16 v[18:21], v[190:193], v[146:149], v[18:21]
	v_mfma_f32_16x16x32_bf16 v[6:9], v[174:177], v[178:181], v[6:9]
	v_mfma_f32_16x16x32_bf16 v[2:5], v[190:193], v[178:181], v[2:5]
	s_setprio 0
	s_add_i32 s8, 0, 0x18000
	v_add_u32_e32 v118, s8, v217
	s_barrier
	ds_read_b128 v[106:109], v118
	ds_read_b128 v[110:113], v118 offset:1024
	ds_read_b128 v[114:117], v118 offset:2048
	ds_read_b128 v[118:121], v118 offset:3072
	s_add_u32 s4, s4, s40
	s_addc_u32 s5, s5, s41
	s_mov_b32 m0, s56
	v_lshl_add_u64 v[174:175], s[4:5], 0, v[196:197]
	ds_read_b128 v[126:129], v235 offset:32768
	ds_read_b128 v[130:133], v235 offset:33792
	ds_read_b128 v[134:137], v235 offset:34816
	ds_read_b128 v[138:141], v235 offset:35840
	ds_read_b128 v[142:145], v235 offset:36864
	ds_read_b128 v[146:149], v235 offset:37888
	ds_read_b128 v[150:153], v235 offset:38912
	ds_read_b128 v[170:173], v235 offset:39936
	global_load_lds_dwordx4 v[174:175], off
	v_lshl_add_u64 v[174:175], s[4:5], 0, v[198:199]
	s_mov_b32 m0, s67
	s_nop 0
	global_load_lds_dwordx4 v[174:175], off
	s_waitcnt lgkmcnt(8)
	s_waitcnt lgkmcnt(0)
	v_mfma_f32_16x16x32_bf16 v[154:157], v[106:109], v[126:129], v[154:157]
	v_mfma_f32_16x16x32_bf16 v[190:193], v[110:113], v[130:133], v[154:157]
	v_mfma_f32_16x16x32_bf16 v[154:157], v[114:117], v[126:129], v[158:161]
	v_mfma_f32_16x16x32_bf16 v[186:189], v[118:121], v[130:133], v[154:157]
	s_barrier
	s_waitcnt lgkmcnt(0)
	s_setprio 1
	s_waitcnt lgkmcnt(0)
	v_mfma_f32_16x16x32_bf16 v[154:157], v[106:109], v[134:137], v[166:169]
	v_mfma_f32_16x16x32_bf16 v[174:177], v[110:113], v[138:141], v[154:157]
	v_mfma_f32_16x16x32_bf16 v[154:157], v[114:117], v[134:137], v[162:165]
	v_mfma_f32_16x16x32_bf16 v[94:97], v[106:109], v[142:145], v[94:97]
	v_mfma_f32_16x16x32_bf16 v[90:93], v[114:117], v[142:145], v[90:93]
	v_mfma_f32_16x16x32_bf16 v[78:81], v[106:109], v[150:153], v[78:81]
	v_mfma_f32_16x16x32_bf16 v[74:77], v[114:117], v[150:153], v[74:77]
	v_mfma_f32_16x16x32_bf16 v[162:165], v[118:121], v[138:141], v[154:157]
	v_mfma_f32_16x16x32_bf16 v[94:97], v[110:113], v[146:149], v[94:97]
	v_mfma_f32_16x16x32_bf16 v[90:93], v[118:121], v[146:149], v[90:93]
	v_mfma_f32_16x16x32_bf16 v[78:81], v[110:113], v[170:173], v[78:81]
	v_mfma_f32_16x16x32_bf16 v[74:77], v[118:121], v[170:173], v[74:77]
	s_setprio 0
	s_barrier
	s_add_i32 s4, 0, 0x1c000
	v_add_u32_e32 v178, s4, v217
	s_add_i32 s5, s8, s43
	ds_read_b128 v[154:157], v178
	ds_read_b128 v[158:161], v178 offset:1024
	ds_read_b128 v[166:169], v178 offset:2048
	ds_read_b128 v[206:209], v178 offset:3072
	v_lshl_add_u64 v[178:179], v[210:211], 0, s[60:61]
	s_mov_b32 m0, s5
	s_nop 0
	global_load_lds_dwordx4 v[178:179], off
	v_lshl_add_u64 v[178:179], v[212:213], 0, s[60:61]
	s_add_i32 m0, s5, 0x2000
	s_nop 0
	global_load_lds_dwordx4 v[178:179], off
	s_waitcnt lgkmcnt(0)
	v_mfma_f32_16x16x32_bf16 v[178:181], v[154:157], v[126:129], v[182:185]
	v_mfma_f32_16x16x32_bf16 v[122:125], v[166:169], v[126:129], v[122:125]
	v_mfma_f32_16x16x32_bf16 v[102:105], v[154:157], v[134:137], v[102:105]
	v_mfma_f32_16x16x32_bf16 v[98:101], v[166:169], v[134:137], v[98:101]
	s_barrier
; #define PG8_STAGE(bufoff, gbase, voff) do { _Pragma("unroll") for (int _i = 0; _i < 2; ++_i) \
;         __builtin_amdgcn_global_load_lds((const unsigned*)((const char*)(gbase) + (voff)[_i]), (LAS unsigned*)(lds + (bufoff) + ldsw + _i * 8192), 16, 0, 0); } while (0)
; #define PG8_LDA(dst, b, h) do { _Pragma("unroll") for (int m = 0; m < 4; ++m) _Pragma("unroll") for (int k = 0; k < 2; ++k) dst[m][k] = *(const LAS bf16x8*)(lds + PG8_SA(b, h) + aoff + m * 2048 + k * 1024); } while (0)
; #define PG8_LDB(dst, b, h) do { _Pragma("unroll") for (int n = 0; n < 2; ++n) _Pragma("unroll") for (int k = 0; k < 2; ++k) dst[n][k] = *(const LAS bf16x8*)(lds + PG8_SB(b, h) + boff + n * 2048 + k * 1024); } while (0)
; #define PG8_MMA(ai, bj, At, Bt) do { __builtin_amdgcn_s_setprio(1); _Pragma("unroll") for (int m = 0; m < 4; ++m) _Pragma("unroll") for (int n = 0; n < 2; ++n) _Pragma("unroll") for (int k = 0; k < 2; ++k) \
;         acc[ai][bj][m][n] = __builtin_amdgcn_mfma_f32_16x16x32_bf16(Bt[n][k], At[m][k], acc[ai][bj][m][n], 0, 0, 0); __builtin_amdgcn_s_setprio(0); } while (0)
; #define PG8_WAIT_V(n) asm volatile("s_waitcnt vmcnt(" #n ")" ::: "memory")
; #define PG8_WAIT_L(n) asm volatile("s_waitcnt lgkmcnt(" #n ")" ::: "memory")
; #define PG8_BAR __builtin_amdgcn_s_barrier()
; #define PG8_SCHED __builtin_amdgcn_sched_barrier(0)
; template <class Epi>
; __device__ __forceinline__ void gemm_phase(LAS unsigned char* lds, const Gemm g, const Sched& S, const Epi& E) {
;     ...
;             PG8_LDB(B1, 1, 1); PG8_STAGE(PG8_SB(1, 0), b3, voffB);
;             PG8_BAR; PG8_WAIT_L(0); PG8_MMA(0, 1, At, B1); PG8_BAR;
;             PG8_LDA(At, 1, 1); PG8_STAGE(PG8_SA(1, 0), a3, voffA);
;             PG8_BAR; PG8_WAIT_L(0); PG8_MMA(1, 0, At, B0); PG8_BAR; PG8_SCHED;
;             PG8_STAGE(PG8_SB(1, 1), b3 + hstepB, voffB);
;             PG8_WAIT_V(6); PG8_BAR; PG8_MMA(1, 1, At, B1); PG8_BAR;
;         }
	s_waitcnt lgkmcnt(0)
	s_setprio 1
	s_waitcnt lgkmcnt(0)
	v_mfma_f32_16x16x32_bf16 v[86:89], v[154:157], v[142:145], v[86:89]
	v_mfma_f32_16x16x32_bf16 v[82:85], v[166:169], v[142:145], v[82:85]
	v_mfma_f32_16x16x32_bf16 v[70:73], v[154:157], v[150:153], v[70:73]
	v_mfma_f32_16x16x32_bf16 v[66:69], v[166:169], v[150:153], v[66:69]
	v_mfma_f32_16x16x32_bf16 v[182:185], v[158:161], v[130:133], v[178:181]
	v_mfma_f32_16x16x32_bf16 v[178:181], v[206:209], v[130:133], v[122:125]
	v_mfma_f32_16x16x32_bf16 v[102:105], v[158:161], v[138:141], v[102:105]
	v_mfma_f32_16x16x32_bf16 v[98:101], v[206:209], v[138:141], v[98:101]
	v_mfma_f32_16x16x32_bf16 v[86:89], v[158:161], v[146:149], v[86:89]
	v_mfma_f32_16x16x32_bf16 v[82:85], v[206:209], v[146:149], v[82:85]
	v_mfma_f32_16x16x32_bf16 v[70:73], v[158:161], v[170:173], v[70:73]
	v_mfma_f32_16x16x32_bf16 v[66:69], v[206:209], v[170:173], v[66:69]
	s_setprio 0
	s_mov_b32 m0, s51
	v_lshl_add_u64 v[170:171], v[214:215], 0, s[60:61]
	s_barrier
	ds_read_b128 v[122:125], v235 offset:49152
	ds_read_b128 v[126:129], v235 offset:50176
	ds_read_b128 v[130:133], v235 offset:51200
	ds_read_b128 v[134:137], v235 offset:52224
	ds_read_b128 v[138:141], v235 offset:53248
	ds_read_b128 v[142:145], v235 offset:54272
	ds_read_b128 v[146:149], v235 offset:55296
	ds_read_b128 v[150:153], v235 offset:56320
	global_load_lds_dwordx4 v[170:171], off
	v_lshl_add_u64 v[170:171], v[222:223], 0, s[60:61]
	s_mov_b32 m0, s2
	s_nop 0
	global_load_lds_dwordx4 v[170:171], off
	s_add_i32 s4, s4, s43
	v_lshl_add_u64 v[170:171], v[224:225], 0, s[60:61]
	s_mov_b32 m0, s4
	s_nop 0
	global_load_lds_dwordx4 v[170:171], off
	v_lshl_add_u64 v[170:171], v[226:227], 0, s[60:61]
	s_add_i32 m0, s4, 0x2000
	s_nop 0
	global_load_lds_dwordx4 v[170:171], off
	s_waitcnt vmcnt(6)
	s_waitcnt lgkmcnt(0)
	v_mfma_f32_16x16x32_bf16 v[62:65], v[106:109], v[122:125], v[62:65]
	v_mfma_f32_16x16x32_bf16 v[58:61], v[114:117], v[122:125], v[58:61]
	v_mfma_f32_16x16x32_bf16 v[46:49], v[106:109], v[130:133], v[46:49]
	v_mfma_f32_16x16x32_bf16 v[42:45], v[114:117], v[130:133], v[42:45]
	s_barrier
	s_setprio 1
	v_mfma_f32_16x16x32_bf16 v[30:33], v[106:109], v[138:141], v[30:33]
	v_mfma_f32_16x16x32_bf16 v[26:29], v[114:117], v[138:141], v[26:29]
	v_mfma_f32_16x16x32_bf16 v[14:17], v[106:109], v[146:149], v[14:17]
	v_mfma_f32_16x16x32_bf16 v[10:13], v[114:117], v[146:149], v[10:13]
	v_mfma_f32_16x16x32_bf16 v[62:65], v[110:113], v[126:129], v[62:65]
	v_mfma_f32_16x16x32_bf16 v[58:61], v[118:121], v[126:129], v[58:61]
	v_mfma_f32_16x16x32_bf16 v[46:49], v[110:113], v[134:137], v[46:49]
	v_mfma_f32_16x16x32_bf16 v[42:45], v[118:121], v[134:137], v[42:45]
	v_mfma_f32_16x16x32_bf16 v[30:33], v[110:113], v[142:145], v[30:33]
	v_mfma_f32_16x16x32_bf16 v[26:29], v[118:121], v[142:145], v[26:29]
	v_mfma_f32_16x16x32_bf16 v[14:17], v[110:113], v[150:153], v[14:17]
	v_mfma_f32_16x16x32_bf16 v[10:13], v[118:121], v[150:153], v[10:13]
	v_mfma_f32_16x16x32_bf16 v[54:57], v[154:157], v[122:125], v[54:57]
	v_mfma_f32_16x16x32_bf16 v[50:53], v[166:169], v[122:125], v[50:53]
	v_mfma_f32_16x16x32_bf16 v[38:41], v[154:157], v[130:133], v[38:41]
	v_mfma_f32_16x16x32_bf16 v[34:37], v[166:169], v[130:133], v[34:37]
	v_mfma_f32_16x16x32_bf16 v[22:25], v[154:157], v[138:141], v[22:25]
	v_mfma_f32_16x16x32_bf16 v[18:21], v[166:169], v[138:141], v[18:21]
	v_mfma_f32_16x16x32_bf16 v[6:9], v[154:157], v[146:149], v[6:9]
	v_mfma_f32_16x16x32_bf16 v[2:5], v[166:169], v[146:149], v[2:5]
	v_mfma_f32_16x16x32_bf16 v[54:57], v[158:161], v[126:129], v[54:57]
	v_mfma_f32_16x16x32_bf16 v[50:53], v[206:209], v[126:129], v[50:53]
	v_mfma_f32_16x16x32_bf16 v[38:41], v[158:161], v[134:137], v[38:41]
	v_mfma_f32_16x16x32_bf16 v[34:37], v[206:209], v[134:137], v[34:37]
	v_mfma_f32_16x16x32_bf16 v[22:25], v[158:161], v[142:145], v[22:25]
	v_mfma_f32_16x16x32_bf16 v[18:21], v[206:209], v[142:145], v[18:21]
	v_mfma_f32_16x16x32_bf16 v[6:9], v[158:161], v[150:153], v[6:9]
	v_mfma_f32_16x16x32_bf16 v[2:5], v[206:209], v[150:153], v[2:5]
	s_setprio 0
	s_add_u32 s0, s0, 0x100
	s_addc_u32 s1, s1, 0
	s_add_u32 s34, s34, 0x100
	s_addc_u32 s35, s35, 0
	s_cmp_ge_u32 s14, s73
	s_mov_b32 s4, s14
	s_barrier
	s_cbranch_scc0 .LBB0_719
	v_readfirstlane_b32 s98, v219
	s_nop 1
	s_bitcmp1_b32 s98, 8
	s_cbranch_scc1 .Lresync_x_719
	s_barrier
